# v31 + priority raise also around the QK clusters of the peeled MLA last tile and the stick-breaking tile loop
# baseline (speedup 1.0000x reference)
; #define MFMA(a, b, c) __builtin_amdgcn_mfma_f32_32x32x16_bf16((a), (b), (c), 0, 0, 0)
; template <int DK, int MODE> ...
;     ...
;     if (active) {
;       f32x16 s0, s1;
;       const bf16_t* kb = sK + cur * 64 * LDK + l32 * LDK + h * 8;
;       bf16x8 kf0[NKS], kf1[NKS];
; #pragma unroll
;       for (int ks = 0; ks < NKS; ++ks) { kf0[ks] = *(const bf16x8*)(kb + ks * 16); kf1[ks] = *(const bf16x8*)(kb + 32 * LDK + ks * 16); }
;       if (MODE == 1) {
;         const float* fb = sF + cur * 64 + 4 * h;
; #pragma unroll
;         for (int g = 0; g < 4; ++g) {
;           const f32x4 f0 = *(const f32x4*)(fb + 8 * g), f1 = *(const f32x4*)(fb + 32 + 8 * g);
;           s0[4 * g] = f0.x; s0[4 * g + 1] = f0.y; s0[4 * g + 2] = f0.z; s0[4 * g + 3] = f0.w;
;           s1[4 * g] = f1.x; s1[4 * g + 1] = f1.y; s1[4 * g + 2] = f1.z; s1[4 * g + 3] = f1.w;
;         }
;       } else {
; #pragma unroll
;         for (int e = 0; e < 16; ++e) { s0[e] = 0.f; s1[e] = 0.f; }
;       }
;       __builtin_amdgcn_iglp_opt(0);
;       __builtin_amdgcn_s_setprio(1);
; #pragma unroll
;       for (int ks = 0; ks < NKS; ++ks) { s0 = MFMA(kf0[ks], qf[ks], s0); s1 = MFMA(kf1[ks], qf[ks], s1); }
;       __builtin_amdgcn_s_setprio(0);
;       const bf16_t* vb = sV + cur * 64 * 72 + l32 * 72 + h * 8;
;       bf16x8 vf0[4], vf1[4];
; #pragma unroll
;       for (int j = 0; j < 4; ++j) { vf0[j] = *(const bf16x8*)(vb + j * 16); vf1[j] = *(const bf16x8*)(vb + 32 * 72 + j * 16); }
;       __builtin_amdgcn_sched_barrier(0);
;       const bool need_mask = CAUSAL && (key0 + 63 >= tq0);
;       bf16x8 pf[4];
;       if (MODE != 2) {
;         if (need_mask) {
; #pragma unroll
;           for (int e = 0; e < 16; ++e) {
;             const int key = key0 + 8 * (e >> 2) + 4 * h + (e & 3);
;             if (key > qpos) s0[e] = -1e30f;
;             if (key + 32 > qpos) s1[e] = -1e30f;
;           }
.LBB0_531:
	s_cmp_le_i32 s2, s8
	s_mov_b64 s[8:9], -1
	s_cbranch_scc0 .LBB0_538
	s_and_b32 s8, s10, 1
	s_mul_i32 s9, s8, 0x3400
	v_add_u32_e32 v0, s9, v175
	ds_read_b128 v[2:5], v0 offset:6656
	ds_read_b128 v[6:9], v0
	ds_read_b128 v[10:13], v0 offset:32
	ds_read_b128 v[48:51], v0 offset:6688
	ds_read_b128 v[52:55], v0 offset:64
	ds_read_b128 v[56:59], v0 offset:6720
	ds_read_b128 v[60:63], v0 offset:96
	ds_read_b128 v[64:67], v0 offset:6752
	ds_read_b128 v[68:71], v0 offset:128
	ds_read_b128 v[72:75], v0 offset:6784
	ds_read_b128 v[76:79], v0 offset:160
	ds_read_b128 v[136:139], v0 offset:6816
	s_setprio 1
	s_waitcnt lgkmcnt(10)
	v_mfma_f32_32x32x16_bf16 v[96:111], v[6:9], v[80:83], 0
	s_mulk_i32 s8, 0x2400
	v_add_u32_e32 v0, s8, v157
	ds_read_b128 v[132:135], v0 offset:31232
	ds_read_b128 v[6:9], v0 offset:26720
	v_mfma_f32_32x32x16_bf16 v[80:95], v[2:5], v[80:83], 0
	ds_read_b128 v[2:5], v0 offset:31328
	s_waitcnt lgkmcnt(12)
	v_mfma_f32_32x32x16_bf16 v[96:111], v[10:13], v[128:131], v[96:111]
	ds_read_b128 v[10:13], v0 offset:26688
	s_waitcnt lgkmcnt(12)
	v_mfma_f32_32x32x16_bf16 v[80:95], v[48:51], v[128:131], v[80:95]
	ds_read_b128 v[128:131], v0 offset:26624
	s_waitcnt lgkmcnt(12)
	v_mfma_f32_32x32x16_bf16 v[96:111], v[52:55], v[124:127], v[96:111]
	s_waitcnt lgkmcnt(11)
	v_mfma_f32_32x32x16_bf16 v[80:95], v[56:59], v[124:127], v[80:95]
	ds_read_b128 v[124:127], v0 offset:31264
	s_waitcnt lgkmcnt(11)
	v_mfma_f32_32x32x16_bf16 v[96:111], v[60:63], v[120:123], v[96:111]
	s_waitcnt lgkmcnt(10)
	v_mfma_f32_32x32x16_bf16 v[80:95], v[64:67], v[120:123], v[80:95]
	ds_read_b128 v[120:123], v0 offset:26656
	s_waitcnt lgkmcnt(10)
	v_mfma_f32_32x32x16_bf16 v[96:111], v[68:71], v[116:119], v[96:111]
	s_waitcnt lgkmcnt(9)
	v_mfma_f32_32x32x16_bf16 v[80:95], v[72:75], v[116:119], v[80:95]
	ds_read_b128 v[116:119], v0 offset:31296
	s_waitcnt lgkmcnt(9)
	v_mfma_f32_32x32x16_bf16 v[96:111], v[76:79], v[112:115], v[96:111]
	s_waitcnt lgkmcnt(8)
	v_mfma_f32_32x32x16_bf16 v[80:95], v[136:139], v[112:115], v[80:95]
	s_setprio 0
	s_or_b32 s8, s2, 63
	s_cmp_lt_i32 s8, s1
	s_cbranch_scc1 .LBB0_534
	v_or_b32_e32 v0, s2, v149
	v_or_b32_e32 v14, 32, v0
	v_cmp_le_i32_e32 vcc, v14, v152
	v_or_b32_e32 v14, 33, v0
	s_nop 4
	v_cndmask_b32_e32 v80, v198, v80, vcc
	v_cmp_lt_i32_e32 vcc, v0, v152
	s_nop 1
	v_cndmask_b32_e32 v97, v198, v97, vcc
	v_cmp_le_i32_e32 vcc, v0, v152
	s_nop 1
	v_cndmask_b32_e32 v96, v198, v96, vcc
	v_cmp_le_i32_e32 vcc, v14, v152
	v_or_b32_e32 v14, 2, v0
	s_nop 0
	v_cndmask_b32_e32 v81, v198, v81, vcc
	v_cmp_le_i32_e32 vcc, v14, v152
	v_or_b32_e32 v14, 34, v0
	s_nop 0
	v_cndmask_b32_e32 v98, v198, v98, vcc
	v_cmp_le_i32_e32 vcc, v14, v152
	v_or_b32_e32 v14, 3, v0
	s_nop 0
	v_cndmask_b32_e32 v82, v198, v82, vcc
	v_cmp_le_i32_e32 vcc, v14, v152
	v_or_b32_e32 v14, 35, v0
	s_nop 0
	v_cndmask_b32_e32 v99, v198, v99, vcc
	v_cmp_le_i32_e32 vcc, v14, v152
	v_or_b32_e32 v14, 8, v0
	s_nop 0
	v_cndmask_b32_e32 v83, v198, v83, vcc
	v_cmp_le_i32_e32 vcc, v14, v152
	v_or_b32_e32 v14, 40, v0
	s_nop 0
	v_cndmask_b32_e32 v100, v198, v100, vcc
	v_cmp_le_i32_e32 vcc, v14, v152
	v_or_b32_e32 v14, 9, v0
	s_nop 0
	v_cndmask_b32_e32 v84, v198, v84, vcc
	v_cmp_le_i32_e32 vcc, v14, v152
	v_or_b32_e32 v14, 41, v0
	s_nop 0
	v_cndmask_b32_e32 v101, v198, v101, vcc
	v_cmp_le_i32_e32 vcc, v14, v152
	v_or_b32_e32 v14, 10, v0
	s_nop 0
	v_cndmask_b32_e32 v85, v198, v85, vcc
	v_cmp_le_i32_e32 vcc, v14, v152
	v_or_b32_e32 v14, 42, v0
	s_nop 0
	v_cndmask_b32_e32 v102, v198, v102, vcc
	v_cmp_le_i32_e32 vcc, v14, v152
	v_or_b32_e32 v14, 11, v0
	s_nop 0
	v_cndmask_b32_e32 v86, v198, v86, vcc
	v_cmp_le_i32_e32 vcc, v14, v152
	v_or_b32_e32 v14, 43, v0
	s_nop 0
	v_cndmask_b32_e32 v103, v198, v103, vcc
	v_cmp_le_i32_e32 vcc, v14, v152
	v_or_b32_e32 v14, 16, v0
	s_nop 0
	v_cndmask_b32_e32 v87, v198, v87, vcc
	v_cmp_le_i32_e32 vcc, v14, v152
	v_or_b32_e32 v14, 48, v0
	s_nop 0
	v_cndmask_b32_e32 v104, v198, v104, vcc
	v_cmp_le_i32_e32 vcc, v14, v152
	v_or_b32_e32 v14, 17, v0
	s_nop 0
	v_cndmask_b32_e32 v88, v198, v88, vcc
	v_cmp_le_i32_e32 vcc, v14, v152
	v_or_b32_e32 v14, 49, v0
	s_nop 0
	v_cndmask_b32_e32 v105, v198, v105, vcc
	v_cmp_le_i32_e32 vcc, v14, v152
	v_or_b32_e32 v14, 18, v0
	s_nop 0
	v_cndmask_b32_e32 v89, v198, v89, vcc
	v_cmp_le_i32_e32 vcc, v14, v152
	v_or_b32_e32 v14, 50, v0
	s_nop 0
	v_cndmask_b32_e32 v106, v198, v106, vcc
	v_cmp_le_i32_e32 vcc, v14, v152
	v_or_b32_e32 v14, 19, v0
	s_nop 0
	v_cndmask_b32_e32 v90, v198, v90, vcc
	v_cmp_le_i32_e32 vcc, v14, v152
	v_or_b32_e32 v14, 51, v0
	s_nop 0
	v_cndmask_b32_e32 v107, v198, v107, vcc
	v_cmp_le_i32_e32 vcc, v14, v152
	v_or_b32_e32 v14, 24, v0
	s_nop 0
	v_cndmask_b32_e32 v91, v198, v91, vcc
	v_cmp_le_i32_e32 vcc, v14, v152
	v_or_b32_e32 v14, 56, v0
	s_nop 0
	v_cndmask_b32_e32 v108, v198, v108, vcc
	v_cmp_le_i32_e32 vcc, v14, v152
	v_or_b32_e32 v14, 25, v0
	s_nop 0
	v_cndmask_b32_e32 v92, v198, v92, vcc
	v_cmp_le_i32_e32 vcc, v14, v152
	v_or_b32_e32 v14, 57, v0
	s_nop 0
	v_cndmask_b32_e32 v109, v198, v109, vcc
	v_cmp_le_i32_e32 vcc, v14, v152
	v_or_b32_e32 v14, 26, v0
	s_nop 0
	v_cndmask_b32_e32 v93, v198, v93, vcc
	v_cmp_le_i32_e32 vcc, v14, v152
	v_or_b32_e32 v14, 58, v0
	s_nop 0
	v_cndmask_b32_e32 v110, v198, v110, vcc
	v_cmp_le_i32_e32 vcc, v14, v152
	v_or_b32_e32 v14, 27, v0
	v_or_b32_e32 v0, 59, v0
	v_cndmask_b32_e32 v94, v198, v94, vcc
	v_cmp_le_i32_e32 vcc, v14, v152
	s_nop 1
	v_cndmask_b32_e32 v111, v198, v111, vcc
	v_cmp_le_i32_e32 vcc, v0, v152
	s_nop 1
	v_cndmask_b32_e32 v95, v198, v95, vcc

; template <int DK, int MODE> ...
;     ...
;       __builtin_amdgcn_iglp_opt(0);
;       __builtin_amdgcn_s_setprio(1);
; #pragma unroll
;       for (int ks = 0; ks < NKS; ++ks) { s0 = MFMA(kf0[ks], qf[ks], s0); s1 = MFMA(kf1[ks], qf[ks], s1); }
;       __builtin_amdgcn_s_setprio(0);
;       const bf16_t* vb = sV + cur * 64 * 72 + l32 * 72 + h * 8;
;       bf16x8 vf0[4], vf1[4];
; #pragma unroll
;       for (int j = 0; j < 4; ++j) { vf0[j] = *(const bf16x8*)(vb + j * 16); vf1[j] = *(const bf16x8*)(vb + 32 * 72 + j * 16); }
;       __builtin_amdgcn_sched_barrier(0);
;       const bool need_mask = CAUSAL && (key0 + 63 >= tq0);
;       bf16x8 pf[4];
;       if (MODE != 2) {
;         if (need_mask) {
; #pragma unroll
;           for (int e = 0; e < 16; ++e) {
;             const int key = key0 + 8 * (e >> 2) + 4 * h + (e & 3);
;             if (key > qpos) s0[e] = -1e30f;
;             if (key + 32 > qpos) s1[e] = -1e30f;
;           }
;         }
;         float mx = s0[0];
; #pragma unroll
;         for (int e = 1; e < 16; ++e) mx = fmaxf(mx, s0[e]);
; #pragma unroll
;         for (int e = 0; e < 16; ++e) mx = fmaxf(mx, s1[e]);
;         mx = fmaxf(mx, __shfl_xor(mx, 32));
;         if (__any(mx > m + 8.f)) {
;           const float mnew = fmaxf(m, mx);
;           const float alpha = __builtin_amdgcn_exp2f(m - mnew);
;           m = mnew; lsum *= alpha;
; #pragma unroll
;           for (int e = 0; e < 16; ++e) { o0[e] *= alpha; o1[e] *= alpha; }
;         }
;         float ps0 = 0.f, ps1 = 0.f, ps2 = 0.f, ps3 = 0.f;
; #pragma unroll
;         for (int e = 0; e < 16; e += 4) {
;           s0[e] = __builtin_amdgcn_exp2f(s0[e] - m); s0[e + 1] = __builtin_amdgcn_exp2f(s0[e + 1] - m); s0[e + 2] = __builtin_amdgcn_exp2f(s0[e + 2] - m); s0[e + 3] = __builtin_amdgcn_exp2f(s0[e + 3] - m);
;           ps0 += s0[e]; ps1 += s0[e + 1]; ps2 += s0[e + 2]; ps3 += s0[e + 3];
;         }
; #pragma unroll
;         for (int e = 0; e < 16; e += 4) {
;           s1[e] = __builtin_amdgcn_exp2f(s1[e] - m); s1[e + 1] = __builtin_amdgcn_exp2f(s1[e + 1] - m); s1[e + 2] = __builtin_amdgcn_exp2f(s1[e + 2] - m); s1[e + 3] = __builtin_amdgcn_exp2f(s1[e + 3] - m);
;           ps0 += s1[e]; ps1 += s1[e + 1]; ps2 += s1[e + 2]; ps3 += s1[e + 3];
;         }
;         lsum += (ps0 + ps1) + (ps2 + ps3);
;       } else {
;         f32x16 kp0, kp1;
; #pragma unroll
.LBB0_577:
	s_and_b32 s16, s6, 1
	s_cmp_gt_i32 s29, s12
	s_cbranch_scc1 .LBB0_581
	s_mul_i32 s4, s16, 0x2400
	v_add_u32_e32 v0, s4, v149
	ds_read_b128 v[2:5], v0 offset:4608
	ds_read_b128 v[6:9], v0
	ds_read_b128 v[10:13], v0 offset:32
	ds_read_b128 v[112:115], v0 offset:4640
	ds_read_b128 v[116:119], v0 offset:64
	ds_read_b128 v[120:123], v0 offset:4672
	ds_read_b128 v[124:127], v0 offset:96
	ds_read_b128 v[158:161], v0 offset:4704
	s_setprio 1
	s_waitcnt lgkmcnt(6)
	v_mfma_f32_32x32x16_bf16 v[64:79], v[6:9], v[80:83], 0
	ds_read_b128 v[128:131], v0 offset:23040
	ds_read_b128 v[6:9], v0 offset:18528
	v_mfma_f32_32x32x16_bf16 v[48:63], v[2:5], v[80:83], 0
	ds_read_b128 v[2:5], v0 offset:23136
	s_waitcnt lgkmcnt(8)
	v_mfma_f32_32x32x16_bf16 v[64:79], v[10:13], v[84:87], v[64:79]
	ds_read_b128 v[10:13], v0 offset:18496
	s_waitcnt lgkmcnt(8)
	v_mfma_f32_32x32x16_bf16 v[48:63], v[112:115], v[84:87], v[48:63]
	ds_read_b128 v[112:115], v0 offset:23104
	s_waitcnt lgkmcnt(8)
	v_mfma_f32_32x32x16_bf16 v[64:79], v[116:119], v[88:91], v[64:79]
	ds_read_b128 v[116:119], v0 offset:18464
	s_waitcnt lgkmcnt(8)
	v_mfma_f32_32x32x16_bf16 v[48:63], v[120:123], v[88:91], v[48:63]
	ds_read_b128 v[120:123], v0 offset:23072
	s_waitcnt lgkmcnt(8)
	v_mfma_f32_32x32x16_bf16 v[64:79], v[124:127], v[92:95], v[64:79]
	ds_read_b128 v[124:127], v0 offset:18432
	s_waitcnt lgkmcnt(8)
	v_mfma_f32_32x32x16_bf16 v[48:63], v[158:161], v[92:95], v[48:63]
	s_setprio 0
	s_nop 8
	v_max_f32_e32 v0, v64, v64
	v_min_f32_e32 v0, 0x42a00000, v0
	v_exp_f32_e32 v162, v0
	v_max_f32_e32 v0, v48, v48
	v_max_f32_e32 v15, v65, v65
	v_max_f32_e32 v48, v66, v66
	v_min_f32_e32 v0, 0x42a00000, v0
	v_min_f32_e32 v15, 0x42a00000, v15
	v_min_f32_e32 v48, 0x42a00000, v48
	v_exp_f32_e32 v168, v0
	v_exp_f32_e32 v163, v15
	v_max_f32_e32 v15, v49, v49
	v_exp_f32_e32 v164, v48
	v_max_f32_e32 v48, v50, v50
	v_max_f32_e32 v50, v68, v68
	v_min_f32_e32 v15, 0x42a00000, v15
	v_min_f32_e32 v50, 0x42a00000, v50
	v_exp_f32_e32 v169, v15
	v_max_f32_e32 v49, v67, v67
	v_exp_f32_e32 v172, v50
	v_max_f32_e32 v50, v52, v52
	v_add_f32_e32 v0, 1.0, v162
	v_min_f32_e32 v48, 0x42a00000, v48
	v_min_f32_e32 v49, 0x42a00000, v49
	v_min_f32_e32 v50, 0x42a00000, v50
	v_rcp_f32_e32 v14, v0
	v_add_f32_e32 v0, 1.0, v168
	v_exp_f32_e32 v170, v48
	v_exp_f32_e32 v165, v49
	v_max_f32_e32 v49, v51, v51
	v_exp_f32_e32 v174, v50
	v_max_f32_e32 v50, v69, v69
	v_rcp_f32_e32 v64, v0
	v_add_f32_e32 v0, 1.0, v163
	v_min_f32_e32 v49, 0x42a00000, v49
	v_min_f32_e32 v50, 0x42a00000, v50
	v_rcp_f32_e32 v15, v0
	v_add_f32_e32 v0, 1.0, v169
	v_exp_f32_e32 v171, v49
	v_exp_f32_e32 v173, v50
	v_max_f32_e32 v50, v53, v53
	v_rcp_f32_e32 v65, v0
	v_add_f32_e32 v0, 1.0, v164
	v_min_f32_e32 v50, 0x42a00000, v50
	v_rcp_f32_e32 v48, v0
	v_add_f32_e32 v0, 1.0, v170
	v_exp_f32_e32 v175, v50
	v_max_f32_e32 v50, v70, v70
	v_max_f32_e32 v52, v72, v72
	v_rcp_f32_e32 v66, v0
	v_add_f32_e32 v0, 1.0, v165
	v_min_f32_e32 v50, 0x42a00000, v50
	v_min_f32_e32 v52, 0x42a00000, v52
	v_rcp_f32_e32 v49, v0
	v_add_f32_e32 v0, 1.0, v171
	v_exp_f32_e32 v176, v50
	v_max_f32_e32 v50, v54, v54
	v_max_f32_e32 v51, v71, v71
	v_exp_f32_e32 v72, v52
	v_max_f32_e32 v52, v56, v56
	v_rcp_f32_e32 v67, v0
	v_add_f32_e32 v0, 1.0, v172
	v_min_f32_e32 v50, 0x42a00000, v50
	v_min_f32_e32 v51, 0x42a00000, v51
	v_min_f32_e32 v52, 0x42a00000, v52
	v_rcp_f32_e32 v68, v0
	v_add_f32_e32 v0, 1.0, v174
	v_exp_f32_e32 v184, v50
	v_exp_f32_e32 v177, v51
	v_max_f32_e32 v51, v55, v55
	v_exp_f32_e32 v186, v52
	v_max_f32_e32 v52, v73, v73
	v_rcp_f32_e32 v158, v0
	v_add_f32_e32 v0, 1.0, v173
	v_min_f32_e32 v51, 0x42a00000, v51
	v_min_f32_e32 v52, 0x42a00000, v52
	v_rcp_f32_e32 v69, v0
	v_add_f32_e32 v0, 1.0, v175
	v_exp_f32_e32 v185, v51
	v_exp_f32_e32 v73, v52
	v_max_f32_e32 v52, v57, v57
	v_rcp_f32_e32 v159, v0
	v_add_f32_e32 v0, 1.0, v176
	v_min_f32_e32 v52, 0x42a00000, v52
	v_rcp_f32_e32 v50, v0
	v_add_f32_e32 v0, 1.0, v184
	v_exp_f32_e32 v187, v52
	v_max_f32_e32 v52, v74, v74
	v_max_f32_e32 v56, v76, v76
	v_rcp_f32_e32 v54, v0
	v_add_f32_e32 v0, 1.0, v177
	v_min_f32_e32 v52, 0x42a00000, v52
	v_min_f32_e32 v56, 0x42a00000, v56
	v_rcp_f32_e32 v51, v0
	v_add_f32_e32 v0, 1.0, v185
	v_exp_f32_e32 v74, v52
	v_max_f32_e32 v52, v58, v58
	v_max_f32_e32 v53, v75, v75
	v_exp_f32_e32 v180, v56
	v_max_f32_e32 v56, v60, v60
	v_rcp_f32_e32 v55, v0
	v_add_f32_e32 v0, 1.0, v72
	v_min_f32_e32 v52, 0x42a00000, v52
	v_min_f32_e32 v53, 0x42a00000, v53
	v_min_f32_e32 v56, 0x42a00000, v56
	v_rcp_f32_e32 v70, v0
	v_add_f32_e32 v0, 1.0, v186
	v_exp_f32_e32 v200, v52
	v_exp_f32_e32 v75, v53
	v_max_f32_e32 v53, v59, v59
	v_exp_f32_e32 v202, v56
	v_max_f32_e32 v56, v77, v77
	v_rcp_f32_e32 v160, v0
	v_add_f32_e32 v0, 1.0, v73
	v_min_f32_e32 v53, 0x42a00000, v53
	v_min_f32_e32 v56, 0x42a00000, v56
	v_rcp_f32_e32 v71, v0
	v_add_f32_e32 v0, 1.0, v187
	v_exp_f32_e32 v201, v53
	v_exp_f32_e32 v181, v56
	v_max_f32_e32 v56, v61, v61
	v_rcp_f32_e32 v161, v0
	v_add_f32_e32 v0, 1.0, v74
	v_min_f32_e32 v56, 0x42a00000, v56
	v_rcp_f32_e32 v52, v0
	v_add_f32_e32 v0, 1.0, v200
	v_exp_f32_e32 v203, v56
	v_max_f32_e32 v56, v78, v78
	v_rcp_f32_e32 v58, v0
	v_add_f32_e32 v0, 1.0, v75
	v_min_f32_e32 v56, 0x42a00000, v56
	v_rcp_f32_e32 v53, v0
	v_add_f32_e32 v0, 1.0, v201
	v_exp_f32_e32 v204, v56
	v_max_f32_e32 v56, v62, v62
	v_max_f32_e32 v57, v79, v79
	v_rcp_f32_e32 v59, v0
	v_add_f32_e32 v0, 1.0, v180
	v_min_f32_e32 v56, 0x42a00000, v56
	v_min_f32_e32 v57, 0x42a00000, v57
	v_rcp_f32_e32 v166, v0
	v_add_f32_e32 v0, 1.0, v202
	v_exp_f32_e32 v206, v56
	v_exp_f32_e32 v205, v57
	v_max_f32_e32 v57, v63, v63
	v_rcp_f32_e32 v178, v0
	v_add_f32_e32 v0, 1.0, v181
	v_min_f32_e32 v57, 0x42a00000, v57
	v_rcp_f32_e32 v167, v0
	v_add_f32_e32 v0, 1.0, v203
	v_exp_f32_e32 v207, v57
	v_rcp_f32_e32 v179, v0
	v_add_f32_e32 v0, 1.0, v204
	v_rcp_f32_e32 v56, v0
	v_add_f32_e32 v0, 1.0, v206
	v_rcp_f32_e32 v182, v0
	v_add_f32_e32 v0, 1.0, v205
	v_rcp_f32_e32 v57, v0
	v_add_f32_e32 v0, 1.0, v207
	v_rcp_f32_e32 v183, v0
	s_add_i32 s4, s29, 63
	v_pk_mul_f32 v[162:163], v[162:163], v[14:15]
	v_pk_mul_f32 v[164:165], v[164:165], v[48:49]
	v_pk_mul_f32 v[76:77], v[172:173], v[68:69]
	v_pk_mul_f32 v[78:79], v[176:177], v[50:51]
	v_pk_mul_f32 v[72:73], v[72:73], v[70:71]
	v_pk_mul_f32 v[74:75], v[74:75], v[52:53]
	v_pk_mul_f32 v[60:61], v[180:181], v[166:167]
	v_pk_mul_f32 v[62:63], v[204:205], v[56:57]
	v_pk_mul_f32 v[176:177], v[168:169], v[64:65]
	v_pk_mul_f32 v[180:181], v[170:171], v[66:67]
	v_pk_mul_f32 v[172:173], v[174:175], v[158:159]
	v_pk_mul_f32 v[174:175], v[184:185], v[54:55]
	v_pk_mul_f32 v[168:169], v[186:187], v[160:161]
	v_pk_mul_f32 v[170:171], v[200:201], v[58:59]
	v_pk_mul_f32 v[184:185], v[202:203], v[178:179]
	s_cmp_lt_i32 s4, s79
	v_pk_mul_f32 v[186:187], v[206:207], v[182:183]
	s_cbranch_scc1 .LBB0_580
; template <int DK, int MODE> ...
;     ...
;         if (need_mask) {
; #pragma unroll
;           for (int e = 0; e < 16; ++e) {
;             const int key = key0 + 8 * (e >> 2) + 4 * h + (e & 3);
;             if (key >= qpos) { kp0[e] = 1.f; s0[e] = 0.f; }
;             if (key + 32 >= qpos) { kp1[e] = 1.f; s1[e] = 0.f; }
;           }
;         }
	v_add_u32_e32 v0, s29, v135
	v_add_u32_e32 v157, 32, v0
	v_cmp_lt_i32_e64 s[4:5], v157, v132
	v_add_u32_e32 v157, 1, v0
	v_cmp_lt_i32_e64 s[72:73], v157, v132
	v_add_u32_e32 v157, 33, v0
	v_cmp_lt_i32_e64 s[42:43], v157, v132
	v_add_u32_e32 v157, 2, v0
	v_cmp_lt_i32_e64 s[74:75], v157, v132
	v_add_u32_e32 v157, 34, v0
	v_cmp_lt_i32_e64 s[44:45], v157, v132
	v_add_u32_e32 v157, 3, v0
	v_cmp_lt_i32_e64 s[76:77], v157, v132
	v_add_u32_e32 v157, 35, v0
	v_cmp_lt_i32_e64 s[46:47], v157, v132
	v_add_u32_e32 v157, 8, v0
	v_cmp_lt_i32_e64 s[80:81], v157, v132
	v_add_u32_e32 v157, 40, v0
	v_cmp_lt_i32_e64 s[48:49], v157, v132
	v_add_u32_e32 v157, 9, v0
	s_mov_b64 s[8:9], s[82:83]
	v_cmp_lt_i32_e64 s[82:83], v157, v132
	v_add_u32_e32 v157, 41, v0
	v_cmp_lt_i32_e64 s[50:51], v157, v132
	v_add_u32_e32 v157, 10, v0
	v_cmp_lt_i32_e64 s[84:85], v157, v132
	v_add_u32_e32 v157, 42, v0
	v_cmp_lt_i32_e64 s[52:53], v157, v132
	v_add_u32_e32 v157, 11, v0
	v_cmp_lt_i32_e64 s[86:87], v157, v132
	v_add_u32_e32 v157, 43, v0
	v_cmp_lt_i32_e64 s[54:55], v157, v132
	v_add_u32_e32 v157, 16, v0
	v_cmp_lt_i32_e64 s[88:89], v157, v132
	v_add_u32_e32 v157, 48, v0
	v_cmp_lt_i32_e64 s[56:57], v157, v132
	v_add_u32_e32 v157, 17, v0
	v_cmp_lt_i32_e64 s[90:91], v157, v132
	v_add_u32_e32 v157, 49, v0
	v_cmp_lt_i32_e64 s[58:59], v157, v132
	v_add_u32_e32 v157, 18, v0
	v_cmp_lt_i32_e64 s[92:93], v157, v132
	v_add_u32_e32 v157, 50, v0
	v_cmp_lt_i32_e64 s[60:61], v157, v132
	v_add_u32_e32 v157, 19, v0
	v_cmp_lt_i32_e64 s[94:95], v157, v132
	v_add_u32_e32 v157, 51, v0
	v_cmp_lt_i32_e64 s[62:63], v157, v132
	v_add_u32_e32 v157, 24, v0
	v_cmp_lt_i32_e64 s[96:97], v157, v132
	v_add_u32_e32 v157, 56, v0
	v_cmp_lt_i32_e64 s[64:65], v157, v132
	v_add_u32_e32 v157, 25, v0
	v_cmp_lt_i32_e64 s[98:99], v157, v132
	v_add_u32_e32 v157, 57, v0
	v_cmp_lt_i32_e64 s[66:67], v157, v132
	v_add_u32_e32 v157, 26, v0
	v_cmp_lt_i32_e64 s[6:7], v157, v132
	v_add_u32_e32 v157, 58, v0
	v_cmp_lt_i32_e64 s[68:69], v157, v132
	v_add_u32_e32 v157, 27, v0
	v_cmp_lt_i32_e64 s[70:71], v0, v132
	v_cmp_lt_i32_e32 vcc, v157, v132
	v_add_u32_e32 v0, 59, v0
	s_or_b64 s[6:7], vcc, s[6:7]
	v_cndmask_b32_e32 v63, 0, v63, vcc
	v_cndmask_b32_e32 v57, 1.0, v57, vcc
	v_cmp_lt_i32_e32 vcc, v0, v132
	v_cndmask_b32_e64 v62, 0, v62, s[6:7]
	s_or_b64 s[98:99], s[6:7], s[98:99]
	v_cndmask_b32_e64 v56, 1.0, v56, s[6:7]
	s_or_b64 s[6:7], vcc, s[68:69]
	s_or_b64 s[66:67], s[6:7], s[66:67]
	s_or_b64 s[96:97], s[98:99], s[96:97]
	s_or_b64 s[64:65], s[66:67], s[64:65]
	s_or_b64 s[94:95], s[96:97], s[94:95]
	s_or_b64 s[62:63], s[64:65], s[62:63]
	s_or_b64 s[92:93], s[94:95], s[92:93]
	s_or_b64 s[60:61], s[62:63], s[60:61]
	s_or_b64 s[90:91], s[92:93], s[90:91]
	s_or_b64 s[58:59], s[60:61], s[58:59]
	s_or_b64 s[88:89], s[90:91], s[88:89]
	s_or_b64 s[56:57], s[58:59], s[56:57]
	s_or_b64 s[86:87], s[88:89], s[86:87]
	s_or_b64 s[54:55], s[56:57], s[54:55]
	s_or_b64 s[84:85], s[86:87], s[84:85]
	s_or_b64 s[52:53], s[54:55], s[52:53]
	s_or_b64 s[82:83], s[84:85], s[82:83]
	s_or_b64 s[50:51], s[52:53], s[50:51]
	s_or_b64 s[80:81], s[82:83], s[80:81]
	s_or_b64 s[48:49], s[50:51], s[48:49]
	s_or_b64 s[76:77], s[80:81], s[76:77]
	s_or_b64 s[46:47], s[48:49], s[46:47]
	s_or_b64 s[74:75], s[76:77], s[74:75]
	s_or_b64 s[44:45], s[46:47], s[44:45]
	s_or_b64 s[72:73], s[74:75], s[72:73]
	s_or_b64 s[42:43], s[44:45], s[42:43]
	v_cndmask_b32_e64 v164, 0, v164, s[74:75]
	v_cndmask_b32_e64 v163, 0, v163, s[72:73]
	s_or_b64 s[70:71], s[72:73], s[70:71]
	v_cndmask_b32_e64 v48, 1.0, v48, s[74:75]
	s_movk_i32 s74, 0xe000
	v_cndmask_b32_e64 v15, 1.0, v15, s[72:73]
	s_movk_i32 s72, 0xff80
	s_or_b64 s[4:5], s[42:43], s[4:5]
	v_cndmask_b32_e64 v61, 0, v61, s[98:99]
	v_cndmask_b32_e64 v60, 0, v60, s[96:97]
	v_cndmask_b32_e64 v75, 0, v75, s[94:95]
	v_cndmask_b32_e64 v74, 0, v74, s[92:93]
	v_cndmask_b32_e64 v73, 0, v73, s[90:91]
	v_cndmask_b32_e64 v72, 0, v72, s[88:89]
	v_cndmask_b32_e64 v79, 0, v79, s[86:87]
	v_cndmask_b32_e64 v78, 0, v78, s[84:85]
	v_cndmask_b32_e64 v77, 0, v77, s[82:83]
	v_cndmask_b32_e64 v76, 0, v76, s[80:81]
	v_cndmask_b32_e64 v165, 0, v165, s[76:77]
	v_cndmask_b32_e64 v162, 0, v162, s[70:71]
	v_cndmask_b32_e64 v167, 1.0, v167, s[98:99]
	v_cndmask_b32_e64 v166, 1.0, v166, s[96:97]
	v_cndmask_b32_e64 v53, 1.0, v53, s[94:95]
	v_cndmask_b32_e64 v52, 1.0, v52, s[92:93]
	v_cndmask_b32_e64 v71, 1.0, v71, s[90:91]
	v_cndmask_b32_e64 v70, 1.0, v70, s[88:89]
	v_cndmask_b32_e64 v51, 1.0, v51, s[86:87]
	v_cndmask_b32_e64 v50, 1.0, v50, s[84:85]
	v_cndmask_b32_e64 v69, 1.0, v69, s[82:83]
	s_mov_b64 s[82:83], s[8:9]
	v_cndmask_b32_e64 v68, 1.0, v68, s[80:81]
	s_mov_b32 s80, 0x3a800000
	v_cndmask_b32_e64 v49, 1.0, v49, s[76:77]
	s_mov_b64 s[76:77], 0x2000
	s_mov_b32 s75, -1
	s_mov_b32 s73, -1
	v_cndmask_b32_e64 v14, 1.0, v14, s[70:71]
	v_cndmask_b32_e32 v187, 0, v187, vcc
	v_cndmask_b32_e64 v186, 0, v186, s[6:7]
	v_cndmask_b32_e64 v185, 0, v185, s[66:67]
	v_cndmask_b32_e64 v184, 0, v184, s[64:65]
	v_cndmask_b32_e64 v171, 0, v171, s[62:63]
	v_cndmask_b32_e64 v170, 0, v170, s[60:61]
	v_cndmask_b32_e64 v169, 0, v169, s[58:59]
	v_cndmask_b32_e64 v168, 0, v168, s[56:57]
	v_cndmask_b32_e64 v175, 0, v175, s[54:55]
	v_cndmask_b32_e64 v174, 0, v174, s[52:53]
	v_cndmask_b32_e64 v173, 0, v173, s[50:51]
	v_cndmask_b32_e64 v172, 0, v172, s[48:49]
	v_cndmask_b32_e64 v181, 0, v181, s[46:47]
	v_cndmask_b32_e64 v180, 0, v180, s[44:45]
	v_cndmask_b32_e64 v177, 0, v177, s[42:43]
	v_cndmask_b32_e64 v176, 0, v176, s[4:5]
	v_cndmask_b32_e64 v182, 1.0, v182, s[6:7]
	v_cndmask_b32_e64 v179, 1.0, v179, s[66:67]
	v_cndmask_b32_e64 v178, 1.0, v178, s[64:65]
	v_cndmask_b32_e64 v59, 1.0, v59, s[62:63]
	v_cndmask_b32_e64 v58, 1.0, v58, s[60:61]
	v_cndmask_b32_e64 v161, 1.0, v161, s[58:59]
	v_cndmask_b32_e64 v160, 1.0, v160, s[56:57]
	v_cndmask_b32_e64 v55, 1.0, v55, s[54:55]
	v_cndmask_b32_e64 v54, 1.0, v54, s[52:53]
	v_cndmask_b32_e64 v159, 1.0, v159, s[50:51]
	v_cndmask_b32_e64 v158, 1.0, v158, s[48:49]
	v_cndmask_b32_e64 v67, 1.0, v67, s[46:47]
	v_cndmask_b32_e64 v66, 1.0, v66, s[44:45]
	v_cndmask_b32_e64 v65, 1.0, v65, s[42:43]
	v_cndmask_b32_e64 v64, 1.0, v64, s[4:5]
	v_cndmask_b32_e32 v183, 1.0, v183, vcc
